# phase 3 ssdA: XOR-swizzled transposed LDS tiles (no 8-way bank conflicts on the 16-bit transposing stores), pipelined fragment reads for the state MFMAs
# baseline (speedup 1.0000x reference)
; DI void ssdA_item(const Params& p, int layer, int it, unsigned char* smem) {
;     ...
;     const int r0 = chunk_row0(b, cidx);
;     const bf16_t* UZ = (const bf16_t*)(p.ws + WS_UZ); const float* DT = (const float*)(p.ws + WS_DT);
;     __syncthreads();
;     { const int t = tid & 127, d = tid >> 7; const float dt = DT[(size_t)(r0 + t) * 12 + d * 6 + hd]; const float a = -__expf(p.in[I_ALOG][layer * 12 + d * 6 + hd]); dtv[d * 128 + t] = dt; av[d * 128 + t] = dt * a; }
;     { bf16x8 sv[4];
; #pragma unroll
;       for (int q = 0; q < 4; ++q) { const int i = tid + 256 * q, t = i >> 3, c8 = i & 7; sv[q] = ld8(UZ + (size_t)(r0 + t) * 1024 + 384 + g * 64 + c8 * 8); }
; #pragma unroll
;       for (int q = 0; q < 4; ++q) { const int i = tid + 256 * q, t = i >> 3, c8 = i & 7;
; #pragma unroll
;         for (int j = 0; j < 8; ++j) BT[(c8 * 8 + j) * TS + t] = (bf16_t)sv[q][j]; } }
;     ...
;           for (int q = 0; q < 4; ++q) { const int i = tid + 256 * q, t = i >> 3, c8 = i & 7; sv[q] = ld8(UZ + (size_t)(r0 + t) * 1024 + hd * 64 + c8 * 8); }
.LBB0_1542:
	s_mul_hi_u32 s0, s37, 0x2aaaaaab
	s_mul_i32 s0, s0, 6
	v_and_b32_e32 v0, 0x7f, v10
	v_ashrrev_i32_e32 v12, 7, v10
	s_sub_i32 s42, s37, s0
	v_add_u32_e32 v2, s36, v0
	v_mul_lo_u32 v0, v12, 6
	s_add_i32 s37, s42, s14
	v_ashrrev_i32_e32 v1, 31, v0
	v_mad_u64_u32 v[4:5], s[0:1], v2, 48, s[30:31]
	v_lshl_add_u64 v[4:5], v[0:1], 2, v[4:5]
	v_add_u32_e32 v0, s37, v0
	v_readlane_b32 s44, v255, 7
	v_ashrrev_i32_e32 v1, 31, v0
	v_readlane_b32 s48, v255, 11
	v_readlane_b32 s49, v255, 12
	s_barrier
	s_nop 0
	v_lshl_add_u64 v[0:1], v[0:1], 2, s[48:49]
	global_load_dword v153, v[0:1], off
	s_lshl_b32 s72, s42, 2
	v_lshl_add_u64 v[4:5], v[4:5], 0, s[72:73]
	global_load_dword v154, v[4:5], off
	v_lshl_add_u32 v155, v10, 2, 0
	v_ashrrev_i32_e32 v28, 3, v10
	s_cmp_gt_u32 s42, 2
	s_cselect_b32 s72, 0x80, 0
	v_ashrrev_i32_e32 v11, 6, v10
	v_and_b32_e32 v13, 63, v10
	v_cmp_gt_i32_e32 vcc, 2, v11
	v_readlane_b32 s45, v255, 8
	v_readlane_b32 s46, v255, 9
	v_readlane_b32 s47, v255, 10
	v_readlane_b32 s50, v255, 13
	v_readlane_b32 s51, v255, 14
	v_readlane_b32 s52, v255, 15
	v_readlane_b32 s53, v255, 16
	v_readlane_b32 s54, v255, 17
	v_readlane_b32 s55, v255, 18
	v_readlane_b32 s56, v255, 19
	v_readlane_b32 s57, v255, 20
	v_readlane_b32 s58, v255, 21
	v_readlane_b32 s59, v255, 22
	v_lshlrev_b32_e32 v0, 3, v10
	v_and_b32_e32 v14, 56, v0
	v_add_u32_e32 v0, s36, v28
	v_ashrrev_i32_e32 v1, 31, v0
	v_lshlrev_b64 v[0:1], 11, v[0:1]
	v_lshl_add_u64 v[4:5], s[34:35], 0, v[0:1]
	v_lshl_add_u64 v[4:5], v[4:5], 0, s[72:73]
	v_lshlrev_b32_e32 v2, 1, v14
	v_lshl_add_u64 v[4:5], v[4:5], 0, v[2:3]
	global_load_dwordx4 v[16:19], v[4:5], off offset:768
	v_add_u32_e32 v4, 0x100, v10
	v_ashrrev_i32_e32 v29, 3, v4
	v_add_u32_e32 v4, s36, v29
	v_ashrrev_i32_e32 v5, 31, v4
	v_lshlrev_b64 v[4:5], 11, v[4:5]
	v_lshl_add_u64 v[6:7], s[34:35], 0, v[4:5]
	v_lshl_add_u64 v[6:7], v[6:7], 0, s[72:73]
	v_lshl_add_u64 v[6:7], v[6:7], 0, v[2:3]
	global_load_dwordx4 v[20:23], v[6:7], off offset:768
	v_add_u32_e32 v6, 0x200, v10
	v_ashrrev_i32_e32 v30, 3, v6
	v_add_u32_e32 v6, s36, v30
	v_ashrrev_i32_e32 v7, 31, v6
	v_lshlrev_b64 v[6:7], 11, v[6:7]
	v_lshl_add_u64 v[8:9], s[34:35], 0, v[6:7]
	v_lshl_add_u64 v[8:9], v[8:9], 0, s[72:73]
	v_lshl_add_u64 v[8:9], v[8:9], 0, v[2:3]
	global_load_dwordx4 v[24:27], v[8:9], off offset:768
	v_add_u32_e32 v8, 0x300, v10
	v_ashrrev_i32_e32 v31, 3, v8
	v_add_u32_e32 v8, s36, v31
	v_ashrrev_i32_e32 v9, 31, v8
	v_lshlrev_b64 v[8:9], 11, v[8:9]
	v_lshl_add_u64 v[32:33], s[34:35], 0, v[8:9]
	v_lshl_add_u64 v[32:33], v[32:33], 0, s[72:73]
	v_lshl_add_u64 v[32:33], v[32:33], 0, v[2:3]
	global_load_dwordx4 v[36:39], v[32:33], off offset:768
	s_lshl_b32 s0, s42, 7
	s_add_u32 s0, s34, s0
	s_addc_u32 s1, s35, 0
	v_lshl_add_u64 v[156:157], s[0:1], 0, v[2:3]
	v_lshl_add_u64 v[158:159], v[156:157], 0, v[4:5]
	v_lshl_add_u64 v[160:161], v[156:157], 0, v[6:7]
	v_lshl_add_u64 v[162:163], v[156:157], 0, v[8:9]
	v_lshl_add_u64 v[156:157], v[156:157], 0, v[0:1]
	global_load_dwordx4 v[190:193], v[156:157], off
	global_load_dwordx4 v[194:197], v[158:159], off
	global_load_dwordx4 v[198:201], v[160:161], off
	global_load_dwordx4 v[202:205], v[162:163], off
	s_waitcnt vmcnt(9)
	v_mul_f32_e32 v153, 0x3fb8aa3b, v153
	v_exp_f32_e32 v153, v153
	s_waitcnt vmcnt(8)
	v_mul_f32_e64 v153, v154, -v153
	ds_write2st64_b32 v155, v154, v153 offset0:136 offset1:140
	v_xor_b32_e32 v32, v28, v14
	v_lshl_add_u32 v32, v32, 1, 0
	v_mad_u32_u24 v15, v14, s86, v32
	v_xor_b32_e32 v33, v29, v14
	v_lshl_add_u32 v33, v33, 1, 0
	v_xor_b32_e32 v34, v30, v14
	v_lshl_add_u32 v34, v34, 1, 0
	v_xor_b32_e32 v35, v31, v14
	v_lshl_add_u32 v35, v35, 1, 0
	s_waitcnt vmcnt(7)
	ds_write_b16 v15, v16
	ds_write_b16_d16_hi v15, v16 offset:272
	ds_write_b16 v15, v17 offset:544
	ds_write_b16_d16_hi v15, v17 offset:816
	ds_write_b16 v15, v18 offset:1088
	ds_write_b16_d16_hi v15, v18 offset:1360
	ds_write_b16 v15, v19 offset:1632
	ds_write_b16_d16_hi v15, v19 offset:1904
	v_mad_u32_u24 v15, v14, s86, v33
	s_waitcnt vmcnt(6)
	ds_write_b16 v15, v20
	ds_write_b16_d16_hi v15, v20 offset:272
	ds_write_b16 v15, v21 offset:544
	ds_write_b16_d16_hi v15, v21 offset:816
	ds_write_b16 v15, v22 offset:1088
	ds_write_b16_d16_hi v15, v22 offset:1360
	ds_write_b16 v15, v23 offset:1632
	ds_write_b16_d16_hi v15, v23 offset:1904
	v_mad_u32_u24 v15, v14, s86, v34
	s_waitcnt vmcnt(5)
	ds_write_b16 v15, v24
	ds_write_b16_d16_hi v15, v24 offset:272
	ds_write_b16 v15, v25 offset:544
	ds_write_b16_d16_hi v15, v25 offset:816
	ds_write_b16 v15, v26 offset:1088
	ds_write_b16_d16_hi v15, v26 offset:1360
	ds_write_b16 v15, v27 offset:1632
	ds_write_b16_d16_hi v15, v27 offset:1904
	v_mad_u32_u24 v15, v14, s86, v35
	s_waitcnt vmcnt(4)
	ds_write_b16 v15, v36
	ds_write_b16_d16_hi v15, v36 offset:272
	ds_write_b16 v15, v37 offset:544
	ds_write_b16_d16_hi v15, v37 offset:816
	ds_write_b16 v15, v38 offset:1088
	ds_write_b16_d16_hi v15, v38 offset:1360
	ds_write_b16 v15, v39 offset:1632
	ds_write_b16_d16_hi v15, v39 offset:1904
	s_waitcnt lgkmcnt(0)
	s_barrier
; #define MFMA(a, b, c) __builtin_amdgcn_mfma_f32_32x32x16_bf16((a), (b), (c), 0, 0, 0)
; DI f32x16 zero16() { f32x16 z; _Pragma("unroll") for (int i = 0; i < 16; ++i) z[i] = 0.f; return z; }
; DI void wave_scan128(const float* v, float* out, bool reverse, int lane) {
;     const float v0 = v[2 * lane], v1 = v[2 * lane + 1];
;     float s = v0 + v1;
; #pragma unroll
;     for (int o = 1; o < 64; o <<= 1) { float t = __shfl_up(s, o); if (lane >= o) s += t; }
;     const float total = __shfl(s, 63);
;     if (!reverse) { out[2 * lane] = s - v1; out[2 * lane + 1] = s; }
;     else { out[2 * lane] = total - (s - v0 - v1); out[2 * lane + 1] = total - (s - v1); }
; }
; DI void ssdA_item(const Params& p, int layer, int it, unsigned char* smem) {
;     ...
;         const int pt = wave >> 1, nt = wave & 1;
;         f32x16 acc = zero16();
; #pragma unroll
;         for (int ks = 0; ks < 8; ++ks) acc = MFMA(ld8(XT + (32 * pt + li) * TS + 16 * ks + 8 * lh), ld8(BT + (32 * nt + li) * TS + 16 * ks + 8 * lh), acc);
	s_and_saveexec_b64 s[0:1], vcc
	s_cbranch_execz .LBB0_1544
	v_lshlrev_b32_e32 v15, 9, v11
	v_lshlrev_b32_e32 v16, 3, v13
	v_add3_u32 v15, 0, v15, v16
	ds_read_b64 v[16:17], v15 offset:35840
	v_and_b32_e32 v18, 64, v182
	v_add_u32_e32 v19, -1, v182
	v_cmp_lt_i32_e32 vcc, v19, v18
	v_add_u32_e32 v21, -2, v182
	s_waitcnt lgkmcnt(0)
	v_add_f32_e32 v20, v16, v17
	v_cndmask_b32_e32 v19, v19, v182, vcc
	v_lshlrev_b32_e32 v19, 2, v19
	ds_bpermute_b32 v19, v19, v20
	v_cmp_eq_u32_e32 vcc, 0, v13
	s_waitcnt lgkmcnt(0)
	v_add_f32_e32 v19, v20, v19
	v_cndmask_b32_e32 v19, v19, v20, vcc
	v_cmp_lt_i32_e32 vcc, v21, v18
	s_nop 1
	v_cndmask_b32_e32 v20, v21, v182, vcc
	v_lshlrev_b32_e32 v20, 2, v20
	ds_bpermute_b32 v20, v20, v19
	v_cmp_gt_u32_e32 vcc, 2, v13
	s_waitcnt lgkmcnt(0)
	v_add_f32_e32 v20, v19, v20
	v_cndmask_b32_e32 v19, v20, v19, vcc
	v_add_u32_e32 v20, -4, v182
	v_cmp_lt_i32_e32 vcc, v20, v18
	s_nop 1
	v_cndmask_b32_e32 v20, v20, v182, vcc
	v_lshlrev_b32_e32 v20, 2, v20
	ds_bpermute_b32 v20, v20, v19
	v_cmp_gt_u32_e32 vcc, 4, v13
	s_waitcnt lgkmcnt(0)
	v_add_f32_e32 v20, v19, v20
	v_cndmask_b32_e32 v19, v20, v19, vcc
	v_add_u32_e32 v20, -8, v182
	v_cmp_lt_i32_e32 vcc, v20, v18
	s_nop 1
	v_cndmask_b32_e32 v20, v20, v182, vcc
	v_lshlrev_b32_e32 v20, 2, v20
	ds_bpermute_b32 v20, v20, v19
	v_cmp_gt_u32_e32 vcc, 8, v13
	s_waitcnt lgkmcnt(0)
	v_add_f32_e32 v20, v19, v20
	v_cndmask_b32_e32 v19, v20, v19, vcc
	v_add_u32_e32 v20, -16, v182
	v_cmp_lt_i32_e32 vcc, v20, v18
	s_nop 1
	v_cndmask_b32_e32 v20, v20, v182, vcc
	v_lshlrev_b32_e32 v20, 2, v20
	ds_bpermute_b32 v20, v20, v19
	v_cmp_gt_u32_e32 vcc, 16, v13
	s_waitcnt lgkmcnt(0)
	v_add_f32_e32 v20, v19, v20
	v_cndmask_b32_e32 v19, v20, v19, vcc
	v_subrev_u32_e32 v20, 32, v182
	v_cmp_lt_i32_e32 vcc, v20, v18
	s_nop 1
	v_cndmask_b32_e32 v18, v20, v182, vcc
	v_lshlrev_b32_e32 v18, 2, v18
	ds_bpermute_b32 v18, v18, v19
	v_cmp_gt_u32_e32 vcc, 32, v13
	s_waitcnt lgkmcnt(0)
	v_add_f32_e32 v18, v19, v18
	v_cndmask_b32_e32 v19, v18, v19, vcc
	v_lshl_or_b32 v18, v182, 2, v187
	ds_bpermute_b32 v20, v18, v19
	v_sub_f32_e32 v18, v19, v16
	v_pk_add_f32 v[22:23], v[18:19], v[16:17] op_sel:[0,1] neg_lo:[0,1] neg_hi:[0,1]
	v_sub_f32_e32 v16, v19, v17
	v_cmp_eq_u32_e32 vcc, 1, v11
	s_waitcnt lgkmcnt(0)
	v_pk_add_f32 v[20:21], v[20:21], v[22:23] op_sel_hi:[0,1] neg_lo:[0,1] neg_hi:[0,1]
	v_cndmask_b32_e32 v17, v19, v21, vcc
	v_cndmask_b32_e32 v16, v16, v20, vcc
	ds_write_b64 v15, v[16:17] offset:36864
.LBB0_1544:
	s_or_b64 exec, exec, s[0:1]
	s_lshl_b32 s0, s42, 7
	s_add_u32 s0, s34, s0
	v_and_b32_e32 v16, 31, v10
	v_lshrrev_b32_e32 v13, 5, v13
	s_addc_u32 s1, s35, 0
	v_lshlrev_b32_e32 v11, 5, v11
	v_mul_u32_u24_e32 v36, 0x110, v14
	v_lshl_add_u64 v[14:15], s[0:1], 0, v[2:3]
	v_lshl_or_b32 v2, v12, 5, v16
	v_lshlrev_b32_e32 v17, 4, v13
	v_and_or_b32 v11, v11, 32, v16
	v_lshlrev_b32_e32 v12, 11, v12
	v_lshlrev_b32_e32 v13, 8, v13
	v_lshl_add_u64 v[20:21], v[14:15], 0, v[4:5]
	v_or3_b32 v4, v13, v12, v11
	v_mul_lo_u32 v2, v2, s86
	v_mul_u32_u24_e32 v16, 0x110, v11
	v_ashrrev_i32_e32 v5, 31, v4
	v_add3_u32 v2, 0, v2, v17
	v_add3_u32 v37, 0, v16, v17
	v_sub_u32_e32 v38, v2, v17
	v_sub_u32_e32 v39, v37, v17
	v_bfe_u32 v40, v10, 3, 2
	v_bfe_u32 v41, v10, 7, 1
	v_bfe_u32 v42, v10, 6, 1
	v_bfe_u32 v43, v10, 5, 1
	v_lshl_or_b32 v41, v41, 2, v40
	v_lshl_or_b32 v42, v42, 2, v40
	v_xor_b32_e32 v41, v41, v43
	v_xor_b32_e32 v42, v42, v43
	v_xor_b32_e32 v40, 0, v41
	v_lshl_add_u32 v114, v40, 4, v38
	v_xor_b32_e32 v40, 0, v42
	v_lshl_add_u32 v122, v40, 4, v39
	v_xor_b32_e32 v40, 2, v41
	v_lshl_add_u32 v115, v40, 4, v38
	v_xor_b32_e32 v40, 2, v42
	v_lshl_add_u32 v123, v40, 4, v39
	v_xor_b32_e32 v40, 4, v41
	v_lshl_add_u32 v116, v40, 4, v38
	v_xor_b32_e32 v40, 4, v42
	v_lshl_add_u32 v124, v40, 4, v39
	v_xor_b32_e32 v40, 6, v41
	v_lshl_add_u32 v117, v40, 4, v38
	v_xor_b32_e32 v40, 6, v42
	v_lshl_add_u32 v125, v40, 4, v39
	v_xor_b32_e32 v40, 8, v41
	v_lshl_add_u32 v118, v40, 4, v38
	v_xor_b32_e32 v40, 8, v42
	v_lshl_add_u32 v126, v40, 4, v39
	v_xor_b32_e32 v40, 10, v41
	v_lshl_add_u32 v119, v40, 4, v38
	v_xor_b32_e32 v40, 10, v42
	v_lshl_add_u32 v127, v40, 4, v39
	v_xor_b32_e32 v40, 12, v41
	v_lshl_add_u32 v120, v40, 4, v38
	v_xor_b32_e32 v40, 12, v42
	v_lshl_add_u32 v128, v40, 4, v39
	v_xor_b32_e32 v40, 14, v41
	v_lshl_add_u32 v121, v40, 4, v38
	v_xor_b32_e32 v40, 14, v42
	v_lshl_add_u32 v129, v40, 4, v39
	s_mov_b32 s38, 0
	v_cmp_eq_u32_e64 s[0:1], 0, v10
	v_lshl_add_u64 v[0:1], v[14:15], 0, v[0:1]
	v_lshl_add_u64 v[22:23], v[14:15], 0, v[6:7]
	v_lshl_add_u64 v[24:25], v[14:15], 0, v[8:9]
	v_lshl_add_u64 v[26:27], v[4:5], 2, s[18:19]
	s_mov_b64 s[36:37], -1
	s_waitcnt vmcnt(0) lgkmcnt(0)
	s_barrier
	s_branch .LBB0_1546

; DI float bf2f(bf16_t v) { return __uint_as_float(((unsigned)v) << 16); }
; DI bf16_t f2bf(float x) { unsigned r; asm("v_cvt_pk_bf16_f32 %0, %1, %1" : "=v"(r) : "v"(x)); return (bf16_t)r; }
; DI void ssdA_item(const Params& p, int layer, int it, unsigned char* smem) {
;     ...
;     for (int d = 0; d < 2; ++d) {
;         const float total = d == 0 ? cum[127] : cum[128];
;         { bf16x8 sv[4];
; #pragma unroll
;           for (int q = 0; q < 4; ++q) { const int i = tid + 256 * q, t = i >> 3, c8 = i & 7; sv[q] = ld8(UZ + (size_t)(r0 + t) * 1024 + hd * 64 + c8 * 8); }
; #pragma unroll
;           for (int q = 0; q < 4; ++q) { const int i = tid + 256 * q, t = i >> 3, c8 = i & 7;
;             const float w = __expf(total - cum[d * 128 + t]) * dtv[d * 128 + t];
; #pragma unroll
;             for (int j = 0; j < 8; ++j) XT[(c8 * 8 + j) * TS + t] = f2bf(bf2f((bf16_t)sv[q][j]) * w); } }
.LBB0_1546:
	v_mov_b64_e32 v[4:5], v[190:191]
	v_mov_b64_e32 v[6:7], v[192:193]
	v_mov_b64_e32 v[8:9], v[194:195]
	v_mov_b64_e32 v[10:11], v[196:197]
	s_mov_b64 s[40:41], src_shared_base
	s_cmp_lg_u32 0, -1
	s_cselect_b32 s40, 0, 0
	s_cselect_b32 s39, s41, 0
	s_add_u32 s40, s40, 0x91fc
	s_addc_u32 s41, s39, 0
	s_cmp_lg_u64 s[40:41], 0
	s_cselect_b32 s39, s40, -1
	s_add_i32 s43, 0, 0x9200
	s_and_b64 s[40:41], s[36:37], exec
	s_cselect_b32 s39, s39, s43
	s_lshl_b32 s40, s38, 7
	v_mov_b32_e32 v12, s39
	v_add_u32_e32 v13, s40, v28
	v_add_u32_e32 v14, s40, v29
	ds_read_b32 v38, v12
	v_lshl_add_u32 v12, v13, 2, 0
	v_lshl_add_u32 v13, v14, 2, 0
	ds_read2st64_b32 v[40:41], v12 offset0:136 offset1:144
	ds_read2st64_b32 v[42:43], v13 offset0:136 offset1:144
	v_mov_b64_e32 v[12:13], v[198:199]
	v_mov_b64_e32 v[14:15], v[200:201]
	v_mov_b64_e32 v[16:17], v[202:203]
	v_mov_b64_e32 v[18:19], v[204:205]
	v_add_u32_e32 v44, v33, v36
	s_lshl_b32 s38, s38, 2
	s_waitcnt lgkmcnt(1)
	v_sub_f32_e32 v39, v38, v41
	s_waitcnt lgkmcnt(0)
	v_sub_f32_e32 v41, v38, v43
	v_mul_f32_e32 v39, 0x3fb8aa3b, v39
	v_mul_f32_e32 v41, 0x3fb8aa3b, v41
	v_exp_f32_e32 v39, v39
	v_exp_f32_e32 v41, v41
	v_add_u32_e32 v43, v32, v36
	s_add_i32 s38, s38, s13
	v_mul_f32_e32 v39, v40, v39
	v_mul_f32_e32 v40, v42, v41
	s_mul_i32 s38, s38, 6
	s_add_i32 s38, s38, s42
	s_mul_hi_u32 s39, s38, 34
	s_mul_i32 s38, s38, 34
	s_add_u32 s38, s38, s11
	s_addc_u32 s39, s39, 0
	v_lshlrev_b32_e32 v41, 16, v4
	v_and_b32_e32 v4, 0xffff0000, v4
	v_lshlrev_b32_e32 v42, 16, v5
	v_and_b32_e32 v5, 0xffff0000, v5
	v_lshlrev_b32_e32 v45, 16, v6
	v_and_b32_e32 v6, 0xffff0000, v6
	v_lshlrev_b32_e32 v46, 16, v7
	v_and_b32_e32 v7, 0xffff0000, v7
	v_lshlrev_b32_e32 v47, 16, v8
	v_and_b32_e32 v8, 0xffff0000, v8
	v_lshlrev_b32_e32 v48, 16, v9
	v_and_b32_e32 v9, 0xffff0000, v9
	v_mul_f32_e32 v41, v39, v41
	v_mul_f32_e32 v4, v39, v4
	v_lshlrev_b32_e32 v49, 16, v10
	v_mul_f32_e32 v42, v39, v42
	v_mul_f32_e32 v5, v39, v5
	v_mul_f32_e32 v45, v39, v45
	v_mul_f32_e32 v6, v39, v6
	v_mul_f32_e32 v46, v39, v46
	v_mul_f32_e32 v7, v39, v7
	v_mul_f32_e32 v39, v40, v47
	v_mul_f32_e32 v8, v40, v8
	v_mul_f32_e32 v47, v40, v48
	v_mul_f32_e32 v9, v40, v9
	v_cvt_pk_bf16_f32 v41, v41, v41
	v_cvt_pk_bf16_f32 v4, v4, v4
	v_mul_f32_e32 v48, v40, v49
	v_cvt_pk_bf16_f32 v42, v42, v42
	v_cvt_pk_bf16_f32 v5, v5, v5
	v_cvt_pk_bf16_f32 v45, v45, v45
	v_cvt_pk_bf16_f32 v6, v6, v6
	v_cvt_pk_bf16_f32 v46, v46, v46
	v_cvt_pk_bf16_f32 v7, v7, v7
	v_cvt_pk_bf16_f32 v39, v39, v39
	v_cvt_pk_bf16_f32 v8, v8, v8
	v_cvt_pk_bf16_f32 v47, v47, v47
	v_cvt_pk_bf16_f32 v9, v9, v9
	ds_write_b16 v43, v41 offset:17408
	ds_write_b16 v43, v4 offset:17680
	ds_write_b16 v43, v42 offset:17952
	ds_write_b16 v43, v5 offset:18224
	ds_write_b16 v43, v45 offset:18496
	ds_write_b16 v43, v6 offset:18768
	ds_write_b16 v43, v46 offset:19040
	ds_write_b16 v43, v7 offset:19312
	ds_write_b16 v44, v39 offset:17408
	ds_write_b16 v44, v8 offset:17680
	ds_write_b16 v44, v47 offset:17952
	ds_write_b16 v44, v9 offset:18224
	v_cvt_pk_bf16_f32 v4, v48, v48
	ds_write_b16 v44, v4 offset:18496
	v_and_b32_e32 v4, 0xffff0000, v10
	v_mul_f32_e32 v4, v40, v4
	v_cvt_pk_bf16_f32 v4, v4, v4
	ds_write_b16 v44, v4 offset:18768
	v_add_u32_e32 v4, s40, v30
	v_lshl_add_u32 v4, v4, 2, 0
	ds_read2st64_b32 v[4:5], v4 offset0:136 offset1:144
	v_lshlrev_b32_e32 v6, 16, v11
	v_mul_f32_e32 v6, v40, v6
	v_cvt_pk_bf16_f32 v6, v6, v6
	ds_write_b16 v44, v6 offset:19040
	s_waitcnt lgkmcnt(1)
	v_sub_f32_e32 v5, v38, v5
	v_mul_f32_e32 v5, 0x3fb8aa3b, v5
	v_exp_f32_e32 v5, v5
	v_and_b32_e32 v6, 0xffff0000, v11
	v_mul_f32_e32 v6, v40, v6
	v_cvt_pk_bf16_f32 v6, v6, v6
	ds_write_b16 v44, v6 offset:19312
	v_mul_f32_e32 v6, v4, v5
	v_lshlrev_b32_e32 v4, 16, v12
	v_mul_f32_e32 v4, v6, v4
	v_cvt_pk_bf16_f32 v4, v4, v4
	v_add_u32_e32 v7, v34, v36
	ds_write_b16 v7, v4 offset:17408
	v_and_b32_e32 v4, 0xffff0000, v12
	v_mul_f32_e32 v4, v6, v4
	v_cvt_pk_bf16_f32 v4, v4, v4
	ds_write_b16 v7, v4 offset:17680
	v_lshlrev_b32_e32 v4, 16, v13
	v_mul_f32_e32 v4, v6, v4
	v_cvt_pk_bf16_f32 v4, v4, v4
	ds_write_b16 v7, v4 offset:17952
	v_and_b32_e32 v4, 0xffff0000, v13
	v_mul_f32_e32 v4, v6, v4
	v_cvt_pk_bf16_f32 v4, v4, v4
	ds_write_b16 v7, v4 offset:18224
	v_lshlrev_b32_e32 v4, 16, v14
	v_mul_f32_e32 v4, v6, v4
	v_cvt_pk_bf16_f32 v4, v4, v4
	ds_write_b16 v7, v4 offset:18496
	v_and_b32_e32 v4, 0xffff0000, v14
	v_mul_f32_e32 v4, v6, v4
	v_cvt_pk_bf16_f32 v4, v4, v4
	ds_write_b16 v7, v4 offset:18768
	v_add_u32_e32 v4, s40, v31
	v_lshl_add_u32 v4, v4, 2, 0
	ds_read2st64_b32 v[4:5], v4 offset0:136 offset1:144
	v_lshlrev_b32_e32 v8, 16, v15
	v_mul_f32_e32 v8, v6, v8
	v_cvt_pk_bf16_f32 v8, v8, v8
	ds_write_b16 v7, v8 offset:19040
	s_waitcnt lgkmcnt(1)
	v_sub_f32_e32 v5, v38, v5
	v_mul_f32_e32 v5, 0x3fb8aa3b, v5
	v_exp_f32_e32 v5, v5
	v_and_b32_e32 v8, 0xffff0000, v15
	v_mul_f32_e32 v6, v6, v8
	v_cvt_pk_bf16_f32 v6, v6, v6
	v_mul_f32_e32 v4, v4, v5
	v_lshlrev_b32_e32 v5, 16, v16
	v_mul_f32_e32 v5, v4, v5
	ds_write_b16 v7, v6 offset:19312
	v_cvt_pk_bf16_f32 v5, v5, v5
	v_add_u32_e32 v6, v35, v36
	ds_write_b16 v6, v5 offset:17408
	v_and_b32_e32 v5, 0xffff0000, v16
	v_mul_f32_e32 v5, v4, v5
	v_cvt_pk_bf16_f32 v5, v5, v5
	ds_write_b16 v6, v5 offset:17680
	v_lshlrev_b32_e32 v5, 16, v17
	v_mul_f32_e32 v5, v4, v5
	v_cvt_pk_bf16_f32 v5, v5, v5
	ds_write_b16 v6, v5 offset:17952
	v_and_b32_e32 v5, 0xffff0000, v17
	v_mul_f32_e32 v5, v4, v5
	v_cvt_pk_bf16_f32 v5, v5, v5
	ds_write_b16 v6, v5 offset:18224
	v_lshlrev_b32_e32 v5, 16, v18
	v_mul_f32_e32 v5, v4, v5
	v_cvt_pk_bf16_f32 v5, v5, v5
	ds_write_b16 v6, v5 offset:18496
	v_and_b32_e32 v5, 0xffff0000, v18
	v_mul_f32_e32 v5, v4, v5
	v_cvt_pk_bf16_f32 v5, v5, v5
	ds_write_b16 v6, v5 offset:18768
	v_lshlrev_b32_e32 v5, 16, v19
	v_mul_f32_e32 v5, v4, v5
	v_cvt_pk_bf16_f32 v5, v5, v5
	ds_write_b16 v6, v5 offset:19040
	v_and_b32_e32 v5, 0xffff0000, v19
	v_mul_f32_e32 v4, v4, v5
	v_cvt_pk_bf16_f32 v4, v4, v4
	ds_write_b16 v6, v4 offset:19312
	s_waitcnt lgkmcnt(0)
	s_barrier
; #define MFMA(a, b, c) __builtin_amdgcn_mfma_f32_32x32x16_bf16((a), (b), (c), 0, 0, 0)
; DI int crow(int reg, int h) { return (reg & 3) + 8 * (reg >> 2) + 4 * h; }
; DI f32x16 zero16() { f32x16 z; _Pragma("unroll") for (int i = 0; i < 16; ++i) z[i] = 0.f; return z; }
; DI void ssdA_item(const Params& p, int layer, int it, unsigned char* smem) {
;     ...
;         const int pt = wave >> 1, nt = wave & 1;
;         f32x16 acc = zero16();
; #pragma unroll
;         for (int ks = 0; ks < 8; ++ks) acc = MFMA(ld8(XT + (32 * pt + li) * TS + 16 * ks + 8 * lh), ld8(BT + (32 * nt + li) * TS + 16 * ks + 8 * lh), acc);
;         float* st = ST + ((((size_t)d * 4 + b) * 6 + hd) * NCHK + cidx) * 4096;
; #pragma unroll
;         for (int reg = 0; reg < 16; ++reg) st[(32 * pt + crow(reg, lh)) * 64 + 32 * nt + li] = acc[reg];
;         if (tid == 0) DEC[(((size_t)d * 4 + b) * 6 + hd) * NCHK + cidx] = __expf(total);
;         __syncthreads();
	ds_read_b128 v[50:53], v114 offset:17408
	ds_read_b128 v[54:57], v122
	ds_read_b128 v[58:61], v115 offset:17408
	ds_read_b128 v[62:65], v123
	ds_read_b128 v[66:69], v116 offset:17408
	ds_read_b128 v[70:73], v124
	ds_read_b128 v[74:77], v117 offset:17408
	ds_read_b128 v[78:81], v125
	ds_read_b128 v[82:85], v118 offset:17408
	ds_read_b128 v[86:89], v126
	ds_read_b128 v[90:93], v119 offset:17408
	ds_read_b128 v[94:97], v127
	s_lshl_b64 s[40:41], s[38:39], 14
	s_waitcnt lgkmcnt(10)
	v_mfma_f32_32x32x16_bf16 v[4:19], v[50:53], v[54:57], 0
	ds_read_b128 v[98:101], v120 offset:17408
	ds_read_b128 v[102:105], v128
	s_waitcnt lgkmcnt(10)
	v_mfma_f32_32x32x16_bf16 v[4:19], v[58:61], v[62:65], v[4:19]
	ds_read_b128 v[106:109], v121 offset:17408
	ds_read_b128 v[110:113], v129
	s_waitcnt lgkmcnt(10)
	v_mfma_f32_32x32x16_bf16 v[4:19], v[66:69], v[70:73], v[4:19]
	s_waitcnt lgkmcnt(8)
	v_mfma_f32_32x32x16_bf16 v[4:19], v[74:77], v[78:81], v[4:19]
	s_waitcnt lgkmcnt(6)
	v_mfma_f32_32x32x16_bf16 v[4:19], v[82:85], v[86:89], v[4:19]
	s_waitcnt lgkmcnt(4)
	v_mfma_f32_32x32x16_bf16 v[4:19], v[90:93], v[94:97], v[4:19]
	s_waitcnt lgkmcnt(2)
	v_mfma_f32_32x32x16_bf16 v[4:19], v[98:101], v[102:105], v[4:19]
	s_waitcnt lgkmcnt(0)
	v_mfma_f32_32x32x16_bf16 v[4:19], v[106:109], v[110:113], v[4:19]
	v_lshl_add_u64 v[40:41], v[26:27], 0, s[40:41]
	s_nop 10
	global_store_dword v[40:41], v4, off
	global_store_dword v[40:41], v5, off offset:256
	global_store_dword v[40:41], v6, off offset:512
	global_store_dword v[40:41], v7, off offset:768
	global_store_dword v[40:41], v8, off offset:2048
	global_store_dword v[40:41], v9, off offset:2304
	global_store_dword v[40:41], v10, off offset:2560
	global_store_dword v[40:41], v11, off offset:2816
	v_add_co_u32_e32 v4, vcc, s82, v40
	s_nop 1
	v_addc_co_u32_e32 v5, vcc, 0, v41, vcc
	global_store_dword v[4:5], v12, off
	global_store_dword v[4:5], v13, off offset:256
	global_store_dword v[4:5], v14, off offset:512
	global_store_dword v[4:5], v15, off offset:768
	global_store_dword v[4:5], v16, off offset:2048
	global_store_dword v[4:5], v17, off offset:2304
	global_store_dword v[4:5], v18, off offset:2560
	global_store_dword v[4:5], v19, off offset:2816
	s_and_saveexec_b64 s[40:41], s[0:1]
	s_cbranch_execz .LBB0_1545
	v_mul_f32_e32 v4, 0x3fb8aa3b, v38
	v_exp_f32_e32 v4, v4
	s_lshl_b64 s[38:39], s[38:39], 2
	s_add_u32 s38, s15, s38
	s_addc_u32 s39, s12, s39
	global_store_dword v3, v4, s[38:39]
	s_branch .LBB0_1545
